# K-group rescale multiplies as 128 v_mul_f32 instead of 64 v_pk_mul_f32 (packed f32 is slow beside the partner half's MFMAs), on top of v16
# baseline (speedup 1.0000x reference)
.LBB0_769:
	s_sub_u32 vcc_lo, s22, s12
	s_subb_u32 vcc_hi, s23, 0
	s_mov_b32 m0, s37
	s_nop 0
	global_load_lds_dwordx4 v214, vcc
	s_mov_b32 m0, s38
	s_nop 0
	global_load_lds_dwordx4 v212, vcc
	ds_read_b128 v[132:135], v231
	ds_read_b128 v[136:139], v231 offset:1024
	ds_read_b128 v[140:143], v231 offset:2048
	ds_read_b128 v[144:147], v231 offset:3072
	ds_read_b128 v[148:151], v231 offset:16384
	ds_read_b128 v[152:155], v231 offset:17408
	ds_read_b128 v[156:159], v231 offset:18432
	ds_read_b128 v[160:163], v231 offset:19456
	ds_read_b128 v[164:167], v197
	ds_read_b128 v[168:171], v197 offset:1024
	ds_read_b128 v[172:175], v197 offset:2048
	ds_read_b128 v[176:179], v197 offset:3072
	ds_read_b128 v[180:183], v197 offset:4096
	ds_read_b128 v[184:187], v197 offset:5120
	ds_read_b128 v[188:191], v197 offset:6144
	ds_read_b128 v[216:219], v197 offset:7168
	s_add_u32 s24, s22, 0x80
	s_addc_u32 s25, s23, 0
	s_add_i32 s57, 0, 0x10000
	s_cmp_eq_u32 s53, s56
	s_cselect_b32 s25, s1, s25
	s_cselect_b32 s24, s0, s24
	s_cselect_b32 s59, s19, s55
	s_cselect_b32 s58, s18, s54
	s_add_i32 s60, 0, 0x14000
	s_add_i32 m0, s33, 0xc000
	s_nop 0
	global_load_lds_dwordx4 v214, s[22:23]
	s_add_i32 m0, s33, 0xe000
	s_nop 0
	global_load_lds_dwordx4 v212, s[22:23]
	s_waitcnt vmcnt(8)
	s_waitcnt lgkmcnt(0)
	v_mfma_f32_16x16x32_bf16 v[126:129], v[132:135], v[164:167], v[126:129]
	v_mfma_f32_16x16x32_bf16 v[126:129], v[136:139], v[168:171], v[126:129]
	s_barrier
	s_setprio 1
	v_mfma_f32_16x16x32_bf16 v[122:125], v[144:147], v[168:171], v[122:125]
	v_mfma_f32_16x16x32_bf16 v[122:125], v[140:143], v[164:167], v[122:125]
	v_mfma_f32_16x16x32_bf16 v[106:109], v[140:143], v[172:175], v[106:109]
	v_mfma_f32_16x16x32_bf16 v[106:109], v[144:147], v[176:179], v[106:109]
	v_mfma_f32_16x16x32_bf16 v[110:113], v[136:139], v[176:179], v[110:113]
	v_mfma_f32_16x16x32_bf16 v[110:113], v[132:135], v[172:175], v[110:113]
	v_mfma_f32_16x16x32_bf16 v[94:97], v[132:135], v[180:183], v[94:97]
	v_mfma_f32_16x16x32_bf16 v[94:97], v[136:139], v[184:187], v[94:97]
	v_mfma_f32_16x16x32_bf16 v[90:93], v[144:147], v[184:187], v[90:93]
	v_mfma_f32_16x16x32_bf16 v[90:93], v[140:143], v[180:183], v[90:93]
	v_mfma_f32_16x16x32_bf16 v[74:77], v[140:143], v[188:191], v[74:77]
	v_mfma_f32_16x16x32_bf16 v[74:77], v[144:147], v[216:219], v[74:77]
	v_mfma_f32_16x16x32_bf16 v[78:81], v[136:139], v[216:219], v[78:81]
	v_mfma_f32_16x16x32_bf16 v[78:81], v[132:135], v[188:191], v[78:81]
	v_mfma_f32_16x16x32_bf16 v[118:121], v[148:151], v[164:167], v[118:121]
	v_mfma_f32_16x16x32_bf16 v[118:121], v[152:155], v[168:171], v[118:121]
	v_mfma_f32_16x16x32_bf16 v[114:117], v[160:163], v[168:171], v[114:117]
	v_mfma_f32_16x16x32_bf16 v[114:117], v[156:159], v[164:167], v[114:117]
	v_mfma_f32_16x16x32_bf16 v[98:101], v[156:159], v[172:175], v[98:101]
	v_mfma_f32_16x16x32_bf16 v[98:101], v[160:163], v[176:179], v[98:101]
	v_mfma_f32_16x16x32_bf16 v[102:105], v[152:155], v[176:179], v[102:105]
	v_mfma_f32_16x16x32_bf16 v[102:105], v[148:151], v[172:175], v[102:105]
	v_mfma_f32_16x16x32_bf16 v[86:89], v[148:151], v[180:183], v[86:89]
	v_mfma_f32_16x16x32_bf16 v[86:89], v[152:155], v[184:187], v[86:89]
	v_mfma_f32_16x16x32_bf16 v[82:85], v[160:163], v[184:187], v[82:85]
	v_mfma_f32_16x16x32_bf16 v[82:85], v[156:159], v[180:183], v[82:85]
	v_mfma_f32_16x16x32_bf16 v[66:69], v[156:159], v[188:191], v[66:69]
	v_mfma_f32_16x16x32_bf16 v[66:69], v[160:163], v[216:219], v[66:69]
	v_mfma_f32_16x16x32_bf16 v[70:73], v[152:155], v[216:219], v[70:73]
	v_mfma_f32_16x16x32_bf16 v[70:73], v[148:151], v[188:191], v[70:73]
	s_setprio 0
	s_barrier
	ds_read_b128 v[164:167], v197 offset:16384
	ds_read_b128 v[168:171], v197 offset:17408
	ds_read_b128 v[172:175], v197 offset:18432
	ds_read_b128 v[176:179], v197 offset:19456
	ds_read_b128 v[180:183], v197 offset:20480
	ds_read_b128 v[184:187], v197 offset:21504
	ds_read_b128 v[188:191], v197 offset:22528
	ds_read_b128 v[216:219], v197 offset:23552
	s_add_i32 s57, s57, s26
	v_lshl_add_u64 v[192:193], s[58:59], 0, v[208:209]
	s_mov_b32 m0, s57
	s_nop 0
	global_load_lds_dwordx4 v208, s[58:59]
	s_add_i32 m0, s57, 0x2000
	v_lshl_add_u64 v[220:221], s[58:59], 0, v[204:205]
	s_add_u32 s58, s58, s12
	s_addc_u32 s59, s59, 0
	s_add_i32 s57, s60, s26
	global_load_lds_dwordx4 v[220:221], off
	v_lshl_add_u64 v[224:225], s[58:59], 0, v[208:209]
	s_mov_b32 m0, s57
	v_lshl_add_u64 v[226:227], s[58:59], 0, v[204:205]
	global_load_lds_dwordx4 v208, s[58:59]
	s_add_i32 m0, s57, 0x2000
	s_nop 0
	global_load_lds_dwordx4 v204, s[58:59]
	s_waitcnt vmcnt(6)
	s_waitcnt lgkmcnt(0)
	v_mfma_f32_16x16x32_bf16 v[62:65], v[132:135], v[164:167], v[62:65]
	v_mfma_f32_16x16x32_bf16 v[62:65], v[136:139], v[168:171], v[62:65]
	s_barrier
	s_setprio 1
	v_mfma_f32_16x16x32_bf16 v[58:61], v[144:147], v[168:171], v[58:61]
	v_mfma_f32_16x16x32_bf16 v[58:61], v[140:143], v[164:167], v[58:61]
	v_mfma_f32_16x16x32_bf16 v[42:45], v[140:143], v[172:175], v[42:45]
	v_mfma_f32_16x16x32_bf16 v[42:45], v[144:147], v[176:179], v[42:45]
	v_mfma_f32_16x16x32_bf16 v[46:49], v[136:139], v[176:179], v[46:49]
	v_mfma_f32_16x16x32_bf16 v[46:49], v[132:135], v[172:175], v[46:49]
	v_mfma_f32_16x16x32_bf16 v[30:33], v[132:135], v[180:183], v[30:33]
	v_mfma_f32_16x16x32_bf16 v[30:33], v[136:139], v[184:187], v[30:33]
	v_mfma_f32_16x16x32_bf16 v[26:29], v[144:147], v[184:187], v[26:29]
	v_mfma_f32_16x16x32_bf16 v[26:29], v[140:143], v[180:183], v[26:29]
	v_mfma_f32_16x16x32_bf16 v[10:13], v[140:143], v[188:191], v[10:13]
	v_mfma_f32_16x16x32_bf16 v[10:13], v[144:147], v[216:219], v[10:13]
	v_mfma_f32_16x16x32_bf16 v[14:17], v[136:139], v[216:219], v[14:17]
	v_mfma_f32_16x16x32_bf16 v[14:17], v[132:135], v[188:191], v[14:17]
	v_mfma_f32_16x16x32_bf16 v[54:57], v[148:151], v[164:167], v[54:57]
	v_mfma_f32_16x16x32_bf16 v[54:57], v[152:155], v[168:171], v[54:57]
	v_mfma_f32_16x16x32_bf16 v[50:53], v[160:163], v[168:171], v[50:53]
	v_mfma_f32_16x16x32_bf16 v[50:53], v[156:159], v[164:167], v[50:53]
	v_mfma_f32_16x16x32_bf16 v[34:37], v[156:159], v[172:175], v[34:37]
	v_mfma_f32_16x16x32_bf16 v[34:37], v[160:163], v[176:179], v[34:37]
	v_mfma_f32_16x16x32_bf16 v[38:41], v[152:155], v[176:179], v[38:41]
	v_mfma_f32_16x16x32_bf16 v[38:41], v[148:151], v[172:175], v[38:41]
	v_mfma_f32_16x16x32_bf16 v[22:25], v[148:151], v[180:183], v[22:25]
	v_mfma_f32_16x16x32_bf16 v[22:25], v[152:155], v[184:187], v[22:25]
	v_mfma_f32_16x16x32_bf16 v[18:21], v[160:163], v[184:187], v[18:21]
	v_mfma_f32_16x16x32_bf16 v[18:21], v[156:159], v[180:183], v[18:21]
	v_mfma_f32_16x16x32_bf16 v[2:5], v[156:159], v[188:191], v[2:5]
	v_mfma_f32_16x16x32_bf16 v[2:5], v[160:163], v[216:219], v[2:5]
	v_mfma_f32_16x16x32_bf16 v[6:9], v[152:155], v[216:219], v[6:9]
	v_mfma_f32_16x16x32_bf16 v[6:9], v[148:151], v[188:191], v[6:9]
	s_setprio 0
	s_barrier
	s_mov_b32 m0, s33
	s_nop 0
	global_load_lds_dwordx4 v210, s[24:25]
	s_mov_b32 m0, s34
	s_nop 0
	global_load_lds_dwordx4 v206, s[24:25]
	ds_read_b128 v[132:135], v231 offset:32768
	ds_read_b128 v[136:139], v231 offset:33792
	ds_read_b128 v[140:143], v231 offset:34816
	ds_read_b128 v[144:147], v231 offset:35840
	ds_read_b128 v[148:151], v231 offset:49152
	ds_read_b128 v[152:155], v231 offset:50176
	ds_read_b128 v[156:159], v231 offset:51200
	ds_read_b128 v[160:163], v231 offset:52224
	ds_read_b128 v[164:167], v197 offset:32768
	ds_read_b128 v[168:171], v197 offset:33792
	ds_read_b128 v[172:175], v197 offset:34816
	ds_read_b128 v[176:179], v197 offset:35840
	ds_read_b128 v[180:183], v197 offset:36864
	ds_read_b128 v[184:187], v197 offset:37888
	ds_read_b128 v[188:191], v197 offset:38912
	ds_read_b128 v[216:219], v197 offset:39936
	s_add_i32 s57, 0, 0x18000
	s_add_i32 s58, 0, 0x1c000
	s_add_u32 s24, s24, s12
	s_addc_u32 s25, s25, 0
	s_mov_b32 m0, s35
	s_nop 0
	global_load_lds_dwordx4 v210, s[24:25]
	s_mov_b32 m0, s36
	s_nop 0
	global_load_lds_dwordx4 v206, s[24:25]
	s_waitcnt vmcnt(8)
	s_waitcnt lgkmcnt(0)
	v_mfma_f32_16x16x32_bf16 v[126:129], v[132:135], v[164:167], v[126:129]
	v_mfma_f32_16x16x32_bf16 v[126:129], v[136:139], v[168:171], v[126:129]
	s_barrier
	s_setprio 1
	v_mfma_f32_16x16x32_bf16 v[122:125], v[144:147], v[168:171], v[122:125]
	v_mfma_f32_16x16x32_bf16 v[122:125], v[140:143], v[164:167], v[122:125]
	v_mfma_f32_16x16x32_bf16 v[106:109], v[140:143], v[172:175], v[106:109]
	v_mfma_f32_16x16x32_bf16 v[106:109], v[144:147], v[176:179], v[106:109]
	v_mfma_f32_16x16x32_bf16 v[110:113], v[136:139], v[176:179], v[110:113]
	v_mfma_f32_16x16x32_bf16 v[110:113], v[132:135], v[172:175], v[110:113]
	v_mfma_f32_16x16x32_bf16 v[94:97], v[132:135], v[180:183], v[94:97]
	v_mfma_f32_16x16x32_bf16 v[94:97], v[136:139], v[184:187], v[94:97]
	v_mfma_f32_16x16x32_bf16 v[90:93], v[144:147], v[184:187], v[90:93]
	v_mfma_f32_16x16x32_bf16 v[90:93], v[140:143], v[180:183], v[90:93]
	v_mfma_f32_16x16x32_bf16 v[74:77], v[140:143], v[188:191], v[74:77]
	v_mfma_f32_16x16x32_bf16 v[74:77], v[144:147], v[216:219], v[74:77]
	v_mfma_f32_16x16x32_bf16 v[78:81], v[136:139], v[216:219], v[78:81]
	v_mfma_f32_16x16x32_bf16 v[78:81], v[132:135], v[188:191], v[78:81]
	v_mfma_f32_16x16x32_bf16 v[118:121], v[148:151], v[164:167], v[118:121]
	v_mfma_f32_16x16x32_bf16 v[118:121], v[152:155], v[168:171], v[118:121]
	v_mfma_f32_16x16x32_bf16 v[114:117], v[160:163], v[168:171], v[114:117]
	v_mfma_f32_16x16x32_bf16 v[114:117], v[156:159], v[164:167], v[114:117]
	v_mfma_f32_16x16x32_bf16 v[98:101], v[156:159], v[172:175], v[98:101]
	v_mfma_f32_16x16x32_bf16 v[98:101], v[160:163], v[176:179], v[98:101]
	v_mfma_f32_16x16x32_bf16 v[102:105], v[152:155], v[176:179], v[102:105]
	v_mfma_f32_16x16x32_bf16 v[102:105], v[148:151], v[172:175], v[102:105]
	v_mfma_f32_16x16x32_bf16 v[86:89], v[148:151], v[180:183], v[86:89]
	v_mfma_f32_16x16x32_bf16 v[86:89], v[152:155], v[184:187], v[86:89]
	v_mfma_f32_16x16x32_bf16 v[82:85], v[160:163], v[184:187], v[82:85]
	v_mfma_f32_16x16x32_bf16 v[82:85], v[156:159], v[180:183], v[82:85]
	v_mfma_f32_16x16x32_bf16 v[66:69], v[156:159], v[188:191], v[66:69]
	v_mfma_f32_16x16x32_bf16 v[66:69], v[160:163], v[216:219], v[66:69]
	v_mfma_f32_16x16x32_bf16 v[70:73], v[152:155], v[216:219], v[70:73]
	v_mfma_f32_16x16x32_bf16 v[70:73], v[148:151], v[188:191], v[70:73]
	s_setprio 0
	s_barrier
	ds_read_b128 v[164:167], v197 offset:49152
	ds_read_b128 v[168:171], v197 offset:50176
	ds_read_b128 v[172:175], v197 offset:51200
	ds_read_b128 v[176:179], v197 offset:52224
	ds_read_b128 v[180:183], v197 offset:53248
	ds_read_b128 v[184:187], v197 offset:54272
	ds_read_b128 v[188:191], v197 offset:55296
	ds_read_b128 v[216:219], v197 offset:56320
	s_add_i32 s24, s57, s26
	v_lshl_add_u64 v[192:193], v[192:193], 0, s[94:95]
	s_mov_b32 m0, s24
	s_nop 0
	global_load_lds_dwordx4 v[192:193], off
	v_lshl_add_u64 v[192:193], v[220:221], 0, s[94:95]
	s_add_i32 m0, s24, 0x2000
	s_add_i32 s24, s58, s26
	global_load_lds_dwordx4 v[192:193], off
	v_lshl_add_u64 v[192:193], v[224:225], 0, s[94:95]
	s_mov_b32 m0, s24
	s_nop 0
	global_load_lds_dwordx4 v[192:193], off
	v_lshl_add_u64 v[192:193], v[226:227], 0, s[94:95]
	s_add_i32 m0, s24, 0x2000
	s_nop 0
	global_load_lds_dwordx4 v[192:193], off
	s_waitcnt vmcnt(6)
	s_waitcnt lgkmcnt(0)
	v_mfma_f32_16x16x32_bf16 v[62:65], v[132:135], v[164:167], v[62:65]
	v_mfma_f32_16x16x32_bf16 v[62:65], v[136:139], v[168:171], v[62:65]
	s_barrier
	s_setprio 1
	v_mfma_f32_16x16x32_bf16 v[58:61], v[144:147], v[168:171], v[58:61]
	v_mfma_f32_16x16x32_bf16 v[58:61], v[140:143], v[164:167], v[58:61]
	v_mfma_f32_16x16x32_bf16 v[42:45], v[140:143], v[172:175], v[42:45]
	v_mfma_f32_16x16x32_bf16 v[42:45], v[144:147], v[176:179], v[42:45]
	v_mfma_f32_16x16x32_bf16 v[46:49], v[136:139], v[176:179], v[46:49]
	v_mfma_f32_16x16x32_bf16 v[46:49], v[132:135], v[172:175], v[46:49]
	v_mfma_f32_16x16x32_bf16 v[30:33], v[132:135], v[180:183], v[30:33]
	v_mfma_f32_16x16x32_bf16 v[30:33], v[136:139], v[184:187], v[30:33]
	v_mfma_f32_16x16x32_bf16 v[26:29], v[144:147], v[184:187], v[26:29]
	v_mfma_f32_16x16x32_bf16 v[26:29], v[140:143], v[180:183], v[26:29]
	v_mfma_f32_16x16x32_bf16 v[10:13], v[140:143], v[188:191], v[10:13]
	v_mfma_f32_16x16x32_bf16 v[10:13], v[144:147], v[216:219], v[10:13]
	v_mfma_f32_16x16x32_bf16 v[14:17], v[136:139], v[216:219], v[14:17]
	v_mfma_f32_16x16x32_bf16 v[14:17], v[132:135], v[188:191], v[14:17]
	v_mfma_f32_16x16x32_bf16 v[54:57], v[148:151], v[164:167], v[54:57]
	v_mfma_f32_16x16x32_bf16 v[54:57], v[152:155], v[168:171], v[54:57]
	v_mfma_f32_16x16x32_bf16 v[50:53], v[160:163], v[168:171], v[50:53]
	v_mfma_f32_16x16x32_bf16 v[50:53], v[156:159], v[164:167], v[50:53]
	v_mfma_f32_16x16x32_bf16 v[34:37], v[156:159], v[172:175], v[34:37]
	v_mfma_f32_16x16x32_bf16 v[34:37], v[160:163], v[176:179], v[34:37]
	v_mfma_f32_16x16x32_bf16 v[38:41], v[152:155], v[176:179], v[38:41]
	v_mfma_f32_16x16x32_bf16 v[38:41], v[148:151], v[172:175], v[38:41]
	v_mfma_f32_16x16x32_bf16 v[22:25], v[148:151], v[180:183], v[22:25]
	v_mfma_f32_16x16x32_bf16 v[22:25], v[152:155], v[184:187], v[22:25]
	v_mfma_f32_16x16x32_bf16 v[18:21], v[160:163], v[184:187], v[18:21]
	v_mfma_f32_16x16x32_bf16 v[18:21], v[156:159], v[180:183], v[18:21]
	v_mfma_f32_16x16x32_bf16 v[2:5], v[156:159], v[188:191], v[2:5]
	v_mfma_f32_16x16x32_bf16 v[2:5], v[160:163], v[216:219], v[2:5]
	v_mfma_f32_16x16x32_bf16 v[6:9], v[152:155], v[216:219], v[6:9]
	v_mfma_f32_16x16x32_bf16 v[6:9], v[148:151], v[188:191], v[6:9]
	s_setprio 0
	s_barrier
	s_and_b32 s24, s56, 6
	s_cmp_eq_u32 s24, 0
	s_cselect_b64 s[58:59], -1, 0
	s_cmp_ge_u32 s56, s53
	s_cselect_b64 s[24:25], -1, 0
	s_cmp_lt_u32 s56, s53
	s_cselect_b64 s[60:61], -1, 0
	s_and_b64 s[58:59], s[58:59], s[60:61]
	s_andn2_b64 vcc, exec, s[58:59]
	s_cbranch_vccnz .LBB0_768
	v_add_u32_e32 v131, 0x400, v130
	v_add_u32_e32 v148, 0x1000, v130
	v_add_u32_e32 v149, 0x1400, v130
	ds_read2_b32 v[132:133], v130 offset1:1
	ds_read2_b32 v[134:135], v130 offset0:128 offset1:129
	ds_read2_b32 v[136:137], v131 offset1:1
	ds_read2_b32 v[138:139], v131 offset0:128 offset1:129
	ds_read2_b32 v[140:141], v148 offset1:1
	ds_read2_b32 v[142:143], v148 offset0:128 offset1:129
	ds_read2_b32 v[144:145], v149 offset1:1
	ds_read2_b32 v[146:147], v149 offset0:128 offset1:129
	s_waitcnt lgkmcnt(0)
	v_rcp_f32_e32 v150, v133
	v_rcp_f32_e32 v151, v135
	v_rcp_f32_e32 v152, v137
	v_rcp_f32_e32 v153, v139
	v_rcp_f32_e32 v154, v141
	v_rcp_f32_e32 v155, v143
	v_rcp_f32_e32 v156, v145
	v_rcp_f32_e32 v157, v147
	v_mul_f32_e32 v132, v132, v150
	v_mul_f32_e32 v134, v134, v151
	v_mul_f32_e32 v136, v136, v152
	v_mul_f32_e32 v138, v138, v153
	v_mul_f32_e32 v140, v140, v154
	v_mul_f32_e32 v142, v142, v155
	v_mul_f32_e32 v144, v144, v156
	v_mul_f32_e32 v146, v146, v157
	v_mul_f32_e32 v128, v132, v128
	v_mul_f32_e32 v129, v132, v129
	v_mul_f32_e32 v126, v132, v126
	v_mul_f32_e32 v127, v132, v127
	v_mul_f32_e32 v124, v132, v124
	v_mul_f32_e32 v125, v132, v125
	v_mul_f32_e32 v122, v132, v122
	v_mul_f32_e32 v123, v132, v123
	v_mul_f32_e32 v120, v132, v120
	v_mul_f32_e32 v121, v132, v121
	v_mul_f32_e32 v118, v132, v118
	v_mul_f32_e32 v119, v132, v119
	v_mul_f32_e32 v116, v132, v116
	v_mul_f32_e32 v117, v132, v117
	v_mul_f32_e32 v114, v132, v114
	v_mul_f32_e32 v115, v132, v115
	v_mul_f32_e32 v112, v134, v112
	v_mul_f32_e32 v113, v134, v113
	v_mul_f32_e32 v110, v134, v110
	v_mul_f32_e32 v111, v134, v111
	v_mul_f32_e32 v108, v134, v108
	v_mul_f32_e32 v109, v134, v109
	v_mul_f32_e32 v106, v134, v106
	v_mul_f32_e32 v107, v134, v107
	v_mul_f32_e32 v104, v134, v104
	v_mul_f32_e32 v105, v134, v105
	v_mul_f32_e32 v102, v134, v102
	v_mul_f32_e32 v103, v134, v103
	v_mul_f32_e32 v100, v134, v100
	v_mul_f32_e32 v101, v134, v101
	v_mul_f32_e32 v98, v134, v98
	v_mul_f32_e32 v99, v134, v99
	v_mul_f32_e32 v96, v136, v96
	v_mul_f32_e32 v97, v136, v97
	v_mul_f32_e32 v94, v136, v94
	v_mul_f32_e32 v95, v136, v95
	v_mul_f32_e32 v92, v136, v92
	v_mul_f32_e32 v93, v136, v93
	v_mul_f32_e32 v90, v136, v90
	v_mul_f32_e32 v91, v136, v91
	v_mul_f32_e32 v88, v136, v88
	v_mul_f32_e32 v89, v136, v89
	v_mul_f32_e32 v86, v136, v86
	v_mul_f32_e32 v87, v136, v87
	v_mul_f32_e32 v84, v136, v84
	v_mul_f32_e32 v85, v136, v85
	v_mul_f32_e32 v82, v136, v82
	v_mul_f32_e32 v83, v136, v83
	v_mul_f32_e32 v80, v138, v80
	v_mul_f32_e32 v81, v138, v81
	v_mul_f32_e32 v78, v138, v78
	v_mul_f32_e32 v79, v138, v79
	v_mul_f32_e32 v76, v138, v76
	v_mul_f32_e32 v77, v138, v77
	v_mul_f32_e32 v74, v138, v74
	v_mul_f32_e32 v75, v138, v75
	v_mul_f32_e32 v72, v138, v72
	v_mul_f32_e32 v73, v138, v73
	v_mul_f32_e32 v70, v138, v70
	v_mul_f32_e32 v71, v138, v71
	v_mul_f32_e32 v68, v138, v68
	v_mul_f32_e32 v69, v138, v69
	v_mul_f32_e32 v66, v138, v66
	v_mul_f32_e32 v67, v138, v67
	v_mul_f32_e32 v64, v140, v64
	v_mul_f32_e32 v65, v140, v65
	v_mul_f32_e32 v62, v140, v62
	v_mul_f32_e32 v63, v140, v63
	v_mul_f32_e32 v60, v140, v60
	v_mul_f32_e32 v61, v140, v61
	v_mul_f32_e32 v58, v140, v58
	v_mul_f32_e32 v59, v140, v59
	v_mul_f32_e32 v56, v140, v56
	v_mul_f32_e32 v57, v140, v57
	v_mul_f32_e32 v54, v140, v54
	v_mul_f32_e32 v55, v140, v55
	v_mul_f32_e32 v52, v140, v52
	v_mul_f32_e32 v53, v140, v53
	v_mul_f32_e32 v50, v140, v50
	v_mul_f32_e32 v51, v140, v51
	v_mul_f32_e32 v48, v142, v48
	v_mul_f32_e32 v49, v142, v49
	v_mul_f32_e32 v46, v142, v46
	v_mul_f32_e32 v47, v142, v47
	v_mul_f32_e32 v44, v142, v44
	v_mul_f32_e32 v45, v142, v45
	v_mul_f32_e32 v42, v142, v42
	v_mul_f32_e32 v43, v142, v43
	v_mul_f32_e32 v40, v142, v40
	v_mul_f32_e32 v41, v142, v41
	v_mul_f32_e32 v38, v142, v38
	v_mul_f32_e32 v39, v142, v39
	v_mul_f32_e32 v36, v142, v36
	v_mul_f32_e32 v37, v142, v37
	v_mul_f32_e32 v34, v142, v34
	v_mul_f32_e32 v35, v142, v35
	v_mul_f32_e32 v32, v144, v32
	v_mul_f32_e32 v33, v144, v33
	v_mul_f32_e32 v30, v144, v30
	v_mul_f32_e32 v31, v144, v31
	v_mul_f32_e32 v28, v144, v28
	v_mul_f32_e32 v29, v144, v29
	v_mul_f32_e32 v26, v144, v26
	v_mul_f32_e32 v27, v144, v27
	v_mul_f32_e32 v24, v144, v24
	v_mul_f32_e32 v25, v144, v25
	v_mul_f32_e32 v22, v144, v22
	v_mul_f32_e32 v23, v144, v23
	v_mul_f32_e32 v20, v144, v20
	v_mul_f32_e32 v21, v144, v21
	v_mul_f32_e32 v18, v144, v18
	v_mul_f32_e32 v19, v144, v19
	v_mul_f32_e32 v16, v146, v16
	v_mul_f32_e32 v17, v146, v17
	v_mul_f32_e32 v14, v146, v14
	v_mul_f32_e32 v15, v146, v15
	v_mul_f32_e32 v12, v146, v12
	v_mul_f32_e32 v13, v146, v13
	v_mul_f32_e32 v10, v146, v10
	v_mul_f32_e32 v11, v146, v11
	v_mul_f32_e32 v8, v146, v8
	v_mul_f32_e32 v9, v146, v9
	v_mul_f32_e32 v6, v146, v6
	v_mul_f32_e32 v7, v146, v7
	v_mul_f32_e32 v4, v146, v4
	v_mul_f32_e32 v5, v146, v5
	v_mul_f32_e32 v2, v146, v2
	v_mul_f32_e32 v3, v146, v3
	s_branch .LBB0_768
